# combination on the shared-B kernel: counted LDS waits + lean A pointers + S4 transpose load remap + Hyena ticket prefetch
# baseline (speedup 1.0000x reference)
; DI float bf2f(u16 v) { return __uint_as_float(((u32)v) << 16); }
; DI void hyena_item_lat(const Params& p, int l, int it) {
;     ...
;   for (int sb = 0; sb < L; sb += 128) {
; #pragma unroll
;     for (int u = 0; u < 4; ++u) {
;       const int s0 = sb + 32 * u;
;       HY_LOADA(a[(0 - 2 * u) & 7], nb + s0)
;       HY_LOADA(a[(1 - 2 * u) & 7], nb - 16 + s0)
;       const bf16x8 bfrag = *(const bf16x8*)(ub + s0);
; #pragma unroll
;       for (int i = 0; i < 8; ++i) acc[i] = __builtin_amdgcn_mfma_f32_16x16x32_bf16(a[(i - 2 * u) & 7].v, bfrag, acc[i], 0, 0, 0);
;     }
;   }
;     ...
;   float ssq = 0.f;
;   for (int t = 0; t < 32; ++t) ssq += WSP(const float, OFF_PART)[(size_t)(f * 32 + t) * 256 + c];
;   const float scale = rsqrtf(ssq + EPSF);
;   const float bias = p.in[I_HYBIAS][l * 256 + c];
;   const u16* X1C = WSP(const u16, OFF_X1C);
;   u16* YM = WSP(u16, OFF_ACT);
;   const int b = l16;
; #pragma unroll
;   for (int i = 0; i < 8; ++i)
; #pragma unroll
;     for (int r = 0; r < 4; ++r) {
;       const int t = tt0 + 16 * i + kg * 4 + r;
;       const size_t row = (size_t)b * TPB + posoff + t;
;       const float uu = bf2f(UT[((size_t)(c * 16 + b)) * TPB + posoff + t]);
.LBB0_1139:
	s_waitcnt vmcnt(0)
	ds_write_b128 v94, v[82:85]
	s_waitcnt lgkmcnt(0)
	s_barrier
	ds_read_b128 v[66:69], v95
	ds_read_b128 v[70:73], v95 offset:1024
	ds_read_b128 v[86:89], v95 offset:2048
	ds_read_b128 v[74:77], v95 offset:3072
	v_xor_b32_e32 v94, 0x1000, v94
	v_xor_b32_e32 v95, 0x1000, v95
	s_mov_b64 s[38:39], 0x100
	s_waitcnt lgkmcnt(3)
	v_mfma_f32_16x16x32_bf16 v[4:7], v[48:51], v[66:69], v[4:7]
	v_mfma_f32_16x16x32_bf16 v[0:3], v[52:55], v[66:69], v[0:3]
	v_mfma_f32_16x16x32_bf16 v[12:15], v[32:35], v[66:69], v[12:15]
	global_load_dwordx4 v[48:51], v[78:79], off offset:64
	global_load_dwordx4 v[52:55], v[80:81], off offset:64
	s_addk_i32 s13, 0x80
	v_mfma_f32_16x16x32_bf16 v[8:11], v[36:39], v[66:69], v[8:11]
	s_cmpk_lt_u32 s13, 0x780
	s_waitcnt lgkmcnt(2)
	v_mfma_f32_16x16x32_bf16 v[4:7], v[32:35], v[70:73], v[4:7]
	global_load_dwordx4 v[32:35], v[78:79], off
	v_mfma_f32_16x16x32_bf16 v[0:3], v[36:39], v[70:73], v[0:3]
	global_load_dwordx4 v[36:39], v[80:81], off
	v_mfma_f32_16x16x32_bf16 v[20:23], v[40:43], v[66:69], v[20:23]
	v_mfma_f32_16x16x32_bf16 v[16:19], v[44:47], v[66:69], v[16:19]
	s_waitcnt vmcnt(1)
	v_mfma_f32_16x16x32_bf16 v[28:31], v[32:35], v[66:69], v[28:31]
	s_waitcnt vmcnt(0)
	v_mfma_f32_16x16x32_bf16 v[24:27], v[36:39], v[66:69], v[24:27]
	global_load_dwordx4 v[82:85], v[90:91], off offset:64
	v_lshl_add_u64 v[90:91], v[90:91], 0, s[38:39]
	v_mfma_f32_16x16x32_bf16 v[12:15], v[40:43], v[70:73], v[12:15]
	v_mfma_f32_16x16x32_bf16 v[8:11], v[44:47], v[70:73], v[8:11]
	v_mfma_f32_16x16x32_bf16 v[20:23], v[32:35], v[70:73], v[20:23]
	v_mfma_f32_16x16x32_bf16 v[16:19], v[36:39], v[70:73], v[16:19]
	v_mfma_f32_16x16x32_bf16 v[28:31], v[48:51], v[70:73], v[28:31]
	v_mfma_f32_16x16x32_bf16 v[24:27], v[52:55], v[70:73], v[24:27]
	s_waitcnt lgkmcnt(1)
	v_mfma_f32_16x16x32_bf16 v[4:7], v[40:43], v[86:89], v[4:7]
	global_load_dwordx4 v[40:43], v[78:79], off offset:192
	v_mfma_f32_16x16x32_bf16 v[0:3], v[44:47], v[86:89], v[0:3]
	global_load_dwordx4 v[44:47], v[80:81], off offset:192
	v_mfma_f32_16x16x32_bf16 v[12:15], v[32:35], v[86:89], v[12:15]
	v_mfma_f32_16x16x32_bf16 v[8:11], v[36:39], v[86:89], v[8:11]
	s_waitcnt lgkmcnt(0)
	v_mfma_f32_16x16x32_bf16 v[4:7], v[32:35], v[74:77], v[4:7]
	global_load_dwordx4 v[32:35], v[78:79], off offset:128
	v_mfma_f32_16x16x32_bf16 v[0:3], v[36:39], v[74:77], v[0:3]
	global_load_dwordx4 v[36:39], v[80:81], off offset:128
	v_lshl_add_u64 v[78:79], v[78:79], 0, s[38:39]
	v_lshl_add_u64 v[80:81], v[80:81], 0, s[38:39]
	v_mfma_f32_16x16x32_bf16 v[20:23], v[48:51], v[86:89], v[20:23]
	v_mfma_f32_16x16x32_bf16 v[16:19], v[52:55], v[86:89], v[16:19]
	v_mfma_f32_16x16x32_bf16 v[12:15], v[48:51], v[74:77], v[12:15]
	v_mfma_f32_16x16x32_bf16 v[8:11], v[52:55], v[74:77], v[8:11]
	s_waitcnt vmcnt(1)
	v_mfma_f32_16x16x32_bf16 v[28:31], v[32:35], v[86:89], v[28:31]
	s_waitcnt vmcnt(0)
	v_mfma_f32_16x16x32_bf16 v[24:27], v[36:39], v[86:89], v[24:27]
	v_mfma_f32_16x16x32_bf16 v[20:23], v[32:35], v[74:77], v[20:23]
	v_mfma_f32_16x16x32_bf16 v[16:19], v[36:39], v[74:77], v[16:19]
	v_mfma_f32_16x16x32_bf16 v[28:31], v[40:43], v[74:77], v[28:31]
	v_mfma_f32_16x16x32_bf16 v[24:27], v[44:47], v[74:77], v[24:27]
	s_cbranch_scc1 .LBB0_1139
	s_waitcnt vmcnt(0)
	v_mov_b64_e32 v[32:33], s[96:97]
	v_mad_i64_i32 v[32:33], s[38:39], v59, s9, v[32:33]
	s_mov_b64 s[38:39], 0x15600200
	s_ashr_i32 s35, s34, 31
	v_lshl_add_u64 v[32:33], v[32:33], 0, s[38:39]
	s_lshl_b64 s[38:39], s[34:35], 2
	s_add_u32 s38, s43, s38
	s_addc_u32 s39, s44, s39
	global_load_dword v38, v173, s[38:39]
	global_load_dword v39, v173, s[38:39] offset:1024
	global_load_dword v40, v173, s[38:39] offset:2048
	global_load_dword v41, v173, s[38:39] offset:3072
	v_mov_b32_e32 v92, 0x1000
	global_load_dword v42, v92, s[38:39]
	global_load_dword v43, v92, s[38:39] offset:1024
	global_load_dword v44, v92, s[38:39] offset:2048
	global_load_dword v45, v92, s[38:39] offset:3072
	v_mov_b32_e32 v92, 0x2000
	global_load_dword v46, v92, s[38:39]
	global_load_dword v47, v92, s[38:39] offset:1024
	global_load_dword v48, v92, s[38:39] offset:2048
	global_load_dword v49, v92, s[38:39] offset:3072
	v_mov_b32_e32 v92, 0x3000
	global_load_dword v50, v92, s[38:39]
	global_load_dword v51, v92, s[38:39] offset:1024
	global_load_dword v52, v92, s[38:39] offset:2048
	global_load_dword v53, v92, s[38:39] offset:3072
	v_mov_b32_e32 v92, 0x4000
	global_load_dword v54, v92, s[38:39]
	global_load_dword v55, v92, s[38:39] offset:1024
	global_load_dword v56, v92, s[38:39] offset:2048
	global_load_dword v57, v92, s[38:39] offset:3072
	v_mov_b32_e32 v92, 0x5000
	global_load_dword v58, v92, s[38:39]
	global_load_dword v65, v92, s[38:39] offset:1024
	global_load_dword v66, v92, s[38:39] offset:2048
	global_load_dword v67, v92, s[38:39] offset:3072
	v_mov_b32_e32 v92, 0x6000
	global_load_dword v68, v92, s[38:39]
	global_load_dword v69, v92, s[38:39] offset:1024
	global_load_dword v70, v92, s[38:39] offset:2048
	global_load_dword v71, v92, s[38:39] offset:3072
	v_mov_b32_e32 v92, 0x7000
	global_load_dword v72, v92, s[38:39]
	global_load_dword v73, v92, s[38:39] offset:1024
	global_load_dword v74, v92, s[38:39] offset:2048
	global_load_dword v75, v92, s[38:39] offset:3072
	v_readlane_b32 s16, v254, 29
	s_lshl_b64 s[36:37], s[36:37], 2
	v_readlane_b32 s18, v254, 31
	v_readlane_b32 s19, v254, 32
	s_add_u32 s36, s18, s36
	s_addc_u32 s37, s19, s37
	global_load_dword v37, v173, s[36:37]
	s_movk_i32 s13, 0x900
	v_lshl_or_b32 v34, v64, 2, v63
	v_mov_b32_e32 v35, 0x100
	v_mad_u32_u24 v172, v62, s13, v35
	v_mov_b32_e32 v35, 0
	v_lshl_add_u64 v[94:95], v[34:35], 1, v[32:33]
	global_load_dwordx2 v[76:77], v[94:95], off
	global_load_dwordx2 v[78:79], v[94:95], off offset:32
	global_load_dwordx2 v[80:81], v[94:95], off offset:64
	global_load_dwordx2 v[82:83], v[94:95], off offset:96
	global_load_dwordx2 v[84:85], v[94:95], off offset:128
	global_load_dwordx2 v[86:87], v[94:95], off offset:160
	global_load_dwordx2 v[88:89], v[94:95], off offset:192
	global_load_dwordx2 v[90:91], v[94:95], off offset:224
	v_readlane_b32 s17, v254, 30
	s_lshl_b64 s[34:35], s[34:35], 1
	v_readlane_b32 s16, v255, 42
	v_readlane_b32 s17, v255, 43
	v_readlane_b32 s20, v254, 33
	v_readlane_b32 s21, v254, 34
	v_readlane_b32 s24, v254, 37
	v_readlane_b32 s18, v254, 10
	s_mov_b64 s[20:21], s[46:47]
	s_mov_b32 s24, s64
	v_readlane_b32 s22, v254, 35
	v_readlane_b32 s23, v254, 36
	v_readlane_b32 s25, v254, 38
	v_readlane_b32 s26, v254, 39
	v_readlane_b32 s27, v254, 40
	v_readlane_b32 s28, v254, 41
	v_readlane_b32 s29, v254, 42
	v_readlane_b32 s30, v254, 43
	v_readlane_b32 s31, v254, 44
	v_readlane_b32 s19, v254, 11
	s_add_u32 s38, s16, s34
	s_addc_u32 s39, s17, s35
	s_add_u32 s36, s6, s34
	s_addc_u32 s37, s7, s35
	v_lshlrev_b32_e32 v142, 13, v62
	v_lshl_add_u32 v142, v34, 2, v142
	s_waitcnt vmcnt(0)
; DI u16 f2bf(float x) { u32 u = __float_as_uint(x); u += 0x7fffu + ((u >> 16) & 1u); return (u16)(u >> 16); }
; DI float bf2f(u16 v) { return __uint_as_float(((u32)v) << 16); }
; DI void hyena_item_lat(const Params& p, int l, int it) {
;     ...
;   float ssq = 0.f;
;   for (int t = 0; t < 32; ++t) ssq += WSP(const float, OFF_PART)[(size_t)(f * 32 + t) * 256 + c];
;   const float scale = rsqrtf(ssq + EPSF);
;   const float bias = p.in[I_HYBIAS][l * 256 + c];
;   const u16* X1C = WSP(const u16, OFF_X1C);
;   u16* YM = WSP(u16, OFF_ACT);
;   const int b = l16;
; #pragma unroll
;   for (int i = 0; i < 8; ++i)
; #pragma unroll
;     for (int r = 0; r < 4; ++r) {
;       const int t = tt0 + 16 * i + kg * 4 + r;
;       const size_t row = (size_t)b * TPB + posoff + t;
;       const float uu = bf2f(UT[((size_t)(c * 16 + b)) * TPB + posoff + t]);
;       const float x1 = bf2f(X1C[row * 256 + c]);
;       YM[row * 1024 + c] = f2bf(x1 * (scale * acc[i][r] + bias * uu));
;     }
	v_add_f32_e32 v36, 0, v38
	v_add_f32_e32 v36, v36, v39
	v_add_f32_e32 v36, v36, v40
	v_add_f32_e32 v36, v36, v41
	v_add_f32_e32 v36, v36, v42
	v_add_f32_e32 v36, v36, v43
	v_add_f32_e32 v36, v36, v44
	v_add_f32_e32 v36, v36, v45
	v_add_f32_e32 v36, v36, v46
	v_add_f32_e32 v36, v36, v47
	v_add_f32_e32 v36, v36, v48
	v_add_f32_e32 v36, v36, v49
	v_add_f32_e32 v36, v36, v50
	v_add_f32_e32 v36, v36, v51
	v_add_f32_e32 v36, v36, v52
	v_add_f32_e32 v36, v36, v53
	v_add_f32_e32 v36, v36, v54
	v_add_f32_e32 v36, v36, v55
	v_add_f32_e32 v36, v36, v56
	v_add_f32_e32 v36, v36, v57
	v_add_f32_e32 v36, v36, v58
	v_add_f32_e32 v36, v36, v65
	v_add_f32_e32 v36, v36, v66
	v_add_f32_e32 v36, v36, v67
	v_add_f32_e32 v36, v36, v68
	v_add_f32_e32 v36, v36, v69
	v_add_f32_e32 v36, v36, v70
	v_add_f32_e32 v36, v36, v71
	v_add_f32_e32 v36, v36, v72
	v_add_f32_e32 v36, v36, v73
	v_add_f32_e32 v36, v36, v74
	v_add_f32_e32 v36, v36, v75
	s_mov_b32 s13, 0x800000
	v_add_f32_e32 v36, 0x358637bd, v36
	v_cmp_gt_f32_e32 vcc, s13, v36
	v_mul_f32_e32 v35, 0x4b800000, v36
	s_movk_i32 s13, 0x900
	s_nop 0
	v_cndmask_b32_e32 v36, v36, v35, vcc
	v_rsq_f32_e32 v36, v36
	s_nop 0
	v_mul_f32_e32 v35, 0x45800000, v36
	v_cndmask_b32_e32 v36, v36, v35, vcc
	v_lshlrev_b32_e32 v92, 16, v76
	v_mul_f32_e32 v92, v37, v92
	v_fmac_f32_e32 v92, v28, v36
	v_mov_b32_e32 v28, v92
	v_and_b32_e32 v92, 0xffff0000, v76
	v_mul_f32_e32 v92, v37, v92
	v_fmac_f32_e32 v92, v29, v36
	v_mov_b32_e32 v29, v92
	v_lshlrev_b32_e32 v92, 16, v77
	v_mul_f32_e32 v92, v37, v92
	v_fmac_f32_e32 v92, v30, v36
	v_mov_b32_e32 v30, v92
	v_and_b32_e32 v92, 0xffff0000, v77
	v_mul_f32_e32 v92, v37, v92
	v_fmac_f32_e32 v92, v31, v36
	v_mov_b32_e32 v31, v92
	v_lshlrev_b32_e32 v92, 16, v78
	v_mul_f32_e32 v92, v37, v92
	v_fmac_f32_e32 v92, v24, v36
	v_mov_b32_e32 v24, v92
	v_and_b32_e32 v92, 0xffff0000, v78
	v_mul_f32_e32 v92, v37, v92
	v_fmac_f32_e32 v92, v25, v36
	v_mov_b32_e32 v25, v92
	v_lshlrev_b32_e32 v92, 16, v79
	v_mul_f32_e32 v92, v37, v92
	v_fmac_f32_e32 v92, v26, v36
	v_mov_b32_e32 v26, v92
	v_and_b32_e32 v92, 0xffff0000, v79
	v_mul_f32_e32 v92, v37, v92
	v_fmac_f32_e32 v92, v27, v36
	v_mov_b32_e32 v27, v92
	v_lshlrev_b32_e32 v92, 16, v80
	v_mul_f32_e32 v92, v37, v92
	v_fmac_f32_e32 v92, v20, v36
	v_mov_b32_e32 v20, v92
	v_and_b32_e32 v92, 0xffff0000, v80
	v_mul_f32_e32 v92, v37, v92
	v_fmac_f32_e32 v92, v21, v36
	v_mov_b32_e32 v21, v92
	v_lshlrev_b32_e32 v92, 16, v81
	v_mul_f32_e32 v92, v37, v92
	v_fmac_f32_e32 v92, v22, v36
	v_mov_b32_e32 v22, v92
	v_and_b32_e32 v92, 0xffff0000, v81
	v_mul_f32_e32 v92, v37, v92
	v_fmac_f32_e32 v92, v23, v36
	v_mov_b32_e32 v23, v92
	v_lshlrev_b32_e32 v92, 16, v82
	v_mul_f32_e32 v92, v37, v92
	v_fmac_f32_e32 v92, v16, v36
	v_mov_b32_e32 v16, v92
	v_and_b32_e32 v92, 0xffff0000, v82
	v_mul_f32_e32 v92, v37, v92
	v_fmac_f32_e32 v92, v17, v36
	v_mov_b32_e32 v17, v92
	v_lshlrev_b32_e32 v92, 16, v83
	v_mul_f32_e32 v92, v37, v92
	v_fmac_f32_e32 v92, v18, v36
	v_mov_b32_e32 v18, v92
	v_and_b32_e32 v92, 0xffff0000, v83
	v_mul_f32_e32 v92, v37, v92
	v_fmac_f32_e32 v92, v19, v36
	v_mov_b32_e32 v19, v92
	v_lshlrev_b32_e32 v92, 16, v84
	v_mul_f32_e32 v92, v37, v92
	v_fmac_f32_e32 v92, v12, v36
	v_mov_b32_e32 v12, v92
	v_and_b32_e32 v92, 0xffff0000, v84
	v_mul_f32_e32 v92, v37, v92
	v_fmac_f32_e32 v92, v13, v36
	v_mov_b32_e32 v13, v92
	v_lshlrev_b32_e32 v92, 16, v85
	v_mul_f32_e32 v92, v37, v92
	v_fmac_f32_e32 v92, v14, v36
	v_mov_b32_e32 v14, v92
	v_and_b32_e32 v92, 0xffff0000, v85
	v_mul_f32_e32 v92, v37, v92
	v_fmac_f32_e32 v92, v15, v36
	v_mov_b32_e32 v15, v92
	v_lshlrev_b32_e32 v92, 16, v86
	v_mul_f32_e32 v92, v37, v92
	v_fmac_f32_e32 v92, v8, v36
	v_mov_b32_e32 v8, v92
	v_and_b32_e32 v92, 0xffff0000, v86
	v_mul_f32_e32 v92, v37, v92
	v_fmac_f32_e32 v92, v9, v36
	v_mov_b32_e32 v9, v92
	v_lshlrev_b32_e32 v92, 16, v87
	v_mul_f32_e32 v92, v37, v92
	v_fmac_f32_e32 v92, v10, v36
	v_mov_b32_e32 v10, v92
	v_and_b32_e32 v92, 0xffff0000, v87
	v_mul_f32_e32 v92, v37, v92
	v_fmac_f32_e32 v92, v11, v36
	v_mov_b32_e32 v11, v92
	v_lshlrev_b32_e32 v92, 16, v88
	v_mul_f32_e32 v92, v37, v92
	v_fmac_f32_e32 v92, v4, v36
	v_mov_b32_e32 v4, v92
	v_and_b32_e32 v92, 0xffff0000, v88
	v_mul_f32_e32 v92, v37, v92
	v_fmac_f32_e32 v92, v5, v36
	v_mov_b32_e32 v5, v92
	v_lshlrev_b32_e32 v92, 16, v89
	v_mul_f32_e32 v92, v37, v92
	v_fmac_f32_e32 v92, v6, v36
	v_mov_b32_e32 v6, v92
	v_and_b32_e32 v92, 0xffff0000, v89
	v_mul_f32_e32 v92, v37, v92
	v_fmac_f32_e32 v92, v7, v36
	v_mov_b32_e32 v7, v92
	v_lshlrev_b32_e32 v92, 16, v90
	v_mul_f32_e32 v92, v37, v92
	v_fmac_f32_e32 v92, v0, v36
	v_mov_b32_e32 v0, v92
	v_and_b32_e32 v92, 0xffff0000, v90
	v_mul_f32_e32 v92, v37, v92
	v_fmac_f32_e32 v92, v1, v36
	v_mov_b32_e32 v1, v92
	v_lshlrev_b32_e32 v92, 16, v91
	v_mul_f32_e32 v92, v37, v92
	v_fmac_f32_e32 v92, v2, v36
	v_mov_b32_e32 v2, v92
	v_and_b32_e32 v92, 0xffff0000, v91
	v_mul_f32_e32 v92, v37, v92
	v_fmac_f32_e32 v92, v3, v36
	v_mov_b32_e32 v3, v92
	s_lshl_b32 s38, s34, 16
	s_add_u32 s38, s96, s38
	s_addc_u32 s39, s97, 0
	global_store_dwordx4 v142, v[28:31], s[38:39]
	global_store_dwordx4 v142, v[24:27], s[38:39] offset:64
	global_store_dwordx4 v142, v[20:23], s[38:39] offset:128
	global_store_dwordx4 v142, v[16:19], s[38:39] offset:192
	global_store_dwordx4 v142, v[12:15], s[38:39] offset:256
	global_store_dwordx4 v142, v[8:11], s[38:39] offset:320
	global_store_dwordx4 v142, v[4:7], s[38:39] offset:384
	global_store_dwordx4 v142, v[0:3], s[38:39] offset:448
